# attention bias init: base computed directly into the accumulator registers (two copy instructions per tile removed)
# speedup vs baseline: 1.0036x; 1.0036x over previous
.LBB0_532:
	s_add_i32 s60, s84, s83
	s_add_i32 s56, s60, 0x7c0
	s_cmp_gt_i32 s56, s79
	s_cbranch_scc1 .LBB0_541
	ds_read_b128 v[4:7], v170
	ds_read_b128 v[8:11], v170 offset:32
	v_add3_u32 v2, s84, v220, 64
	v_cvt_f32_i32_e32 v2, v2
	s_andn2_b64 vcc, exec, s[58:59]
	v_fma_f32 v82, v190, v2, -v185
	v_add_f32_e32 v83, v190, v82
	v_fma_f32 v84, v190, s16, v82
	v_fma_f32 v85, v191, s17, v82
	v_fma_f32 v86, v190, s18, v82
	v_fma_f32 v87, v191, s19, v82
	v_fma_f32 v88, v190, s20, v82
	v_fma_f32 v89, v191, s21, v82
	v_fma_f32 v90, v190, s22, v82
	v_fma_f32 v91, v191, s23, v82
	v_fma_f32 v92, v190, s24, v82
	v_fma_f32 v93, v191, s25, v82
	v_fma_f32 v94, v190, s36, v82
	v_fma_f32 v95, v191, s37, v82
	v_fma_f32 v96, v190, s54, v82
	v_fma_f32 v97, v191, s55, v82
	v_add_f32_e32 v98, v219, v82
	v_add_f32_e32 v99, v190, v98
	s_waitcnt lgkmcnt(1)
	v_mfma_f32_32x32x16_bf16 v[82:97], v[4:7], v[114:117], v[82:97]
	v_fma_f32 v100, v190, s16, v98
	v_fma_f32 v101, v191, s17, v98
	v_fma_f32 v102, v190, s18, v98
	v_fma_f32 v103, v191, s19, v98
	v_fma_f32 v104, v190, s20, v98
	v_fma_f32 v105, v191, s21, v98
	v_fma_f32 v106, v190, s22, v98
	v_fma_f32 v107, v191, s23, v98
	v_fma_f32 v108, v190, s24, v98
	v_fma_f32 v109, v191, s25, v98
	v_fma_f32 v110, v190, s36, v98
	v_fma_f32 v111, v191, s37, v98
	s_waitcnt lgkmcnt(0)
	v_mfma_f32_32x32x16_bf16 v[82:97], v[8:11], v[118:121], v[82:97]
	ds_read_b128 v[4:7], v170 offset:64
	ds_read_b128 v[8:11], v170 offset:96
	v_fma_f32 v112, v190, s54, v98
	v_fma_f32 v113, v191, s55, v98
	s_waitcnt lgkmcnt(1)
	v_mfma_f32_32x32x16_bf16 v[82:97], v[4:7], v[122:125], v[82:97]
	ds_read_b128 v[4:7], v170 offset:8704
	ds_read_b128 v[12:15], v170 offset:8736
	s_waitcnt lgkmcnt(1)
	v_mfma_f32_32x32x16_bf16 v[98:113], v[4:7], v[114:117], v[98:113]
	s_waitcnt lgkmcnt(0)
	v_mfma_f32_32x32x16_bf16 v[98:113], v[12:15], v[118:121], v[98:113]
	v_mfma_f32_32x32x16_bf16 v[82:97], v[8:11], v[126:129], v[82:97]
	ds_read_b128 v[4:7], v170 offset:8768
	ds_read_b128 v[224:227], v170 offset:8800
	ds_read_b64_tr_b16 v[12:13], v207 offset:17408
	ds_read_b64_tr_b16 v[14:15], v207 offset:19968
	ds_read_b64_tr_b16 v[8:9], v207 offset:17472
	ds_read_b64_tr_b16 v[10:11], v207 offset:20032
	s_waitcnt lgkmcnt(5)
	v_mfma_f32_32x32x16_bf16 v[98:113], v[4:7], v[122:125], v[98:113]
	ds_read_b64_tr_b16 v[162:163], v207 offset:17536
	ds_read_b64_tr_b16 v[164:165], v207 offset:20096
	ds_read_b64_tr_b16 v[4:5], v207 offset:17600
	ds_read_b64_tr_b16 v[6:7], v207 offset:20160
	s_waitcnt lgkmcnt(8)
	v_mfma_f32_32x32x16_bf16 v[98:113], v[224:227], v[126:129], v[98:113]
	s_cbranch_vccz .Lmy_maskA

.LBB0_549:
	ds_read_b128 v[4:7], v170 offset:37888
	ds_read_b128 v[8:11], v170 offset:37920
	v_add_u32_e32 v2, s84, v220
	v_cvt_f32_i32_e32 v2, v2
	s_andn2_b64 vcc, exec, s[58:59]
	v_fma_f32 v82, v190, v2, -v185
	v_add_f32_e32 v83, v190, v82
	v_fma_f32 v84, v190, s16, v82
	v_fma_f32 v85, v191, s17, v82
	v_fma_f32 v86, v190, s18, v82
	v_fma_f32 v87, v191, s19, v82
	v_fma_f32 v88, v190, s20, v82
	v_fma_f32 v89, v191, s21, v82
	v_fma_f32 v90, v190, s22, v82
	v_fma_f32 v91, v191, s23, v82
	v_fma_f32 v92, v190, s24, v82
	v_fma_f32 v93, v191, s25, v82
	v_fma_f32 v94, v190, s36, v82
	v_fma_f32 v95, v191, s37, v82
	v_fma_f32 v96, v190, s54, v82
	v_fma_f32 v97, v191, s55, v82
	v_add_f32_e32 v98, v219, v82
	v_add_f32_e32 v99, v190, v98
	s_waitcnt lgkmcnt(1)
	v_mfma_f32_32x32x16_bf16 v[82:97], v[4:7], v[114:117], v[82:97]
	v_fma_f32 v100, v190, s16, v98
	v_fma_f32 v101, v191, s17, v98
	v_fma_f32 v102, v190, s18, v98
	v_fma_f32 v103, v191, s19, v98
	v_fma_f32 v104, v190, s20, v98
	v_fma_f32 v105, v191, s21, v98
	v_fma_f32 v106, v190, s22, v98
	v_fma_f32 v107, v191, s23, v98
	v_fma_f32 v108, v190, s24, v98
	v_fma_f32 v109, v191, s25, v98
	v_fma_f32 v110, v190, s36, v98
	v_fma_f32 v111, v191, s37, v98
	s_waitcnt lgkmcnt(0)
	v_mfma_f32_32x32x16_bf16 v[82:97], v[8:11], v[118:121], v[82:97]
	ds_read_b128 v[4:7], v170 offset:37952
	ds_read_b128 v[8:11], v170 offset:37984
	v_fma_f32 v112, v190, s54, v98
	v_fma_f32 v113, v191, s55, v98
	s_waitcnt lgkmcnt(1)
	v_mfma_f32_32x32x16_bf16 v[82:97], v[4:7], v[122:125], v[82:97]
	ds_read_b128 v[4:7], v170 offset:46592
	ds_read_b128 v[12:15], v170 offset:46624
	s_waitcnt lgkmcnt(1)
	v_mfma_f32_32x32x16_bf16 v[98:113], v[4:7], v[114:117], v[98:113]
	s_waitcnt lgkmcnt(0)
	v_mfma_f32_32x32x16_bf16 v[98:113], v[12:15], v[118:121], v[98:113]
	ds_read_b128 v[4:7], v170 offset:46656
	ds_read_b128 v[224:227], v170 offset:46688
	ds_read_b64_tr_b16 v[162:163], v210 offset:0
	ds_read_b64_tr_b16 v[164:165], v210 offset:2560
	ds_read_b64_tr_b16 v[12:13], v210 offset:64
	ds_read_b64_tr_b16 v[14:15], v210 offset:2624
	s_waitcnt lgkmcnt(5)
	v_mfma_f32_32x32x16_bf16 v[98:113], v[4:7], v[122:125], v[98:113]
	v_mfma_f32_32x32x16_bf16 v[82:97], v[8:11], v[126:129], v[82:97]
	ds_read_b64_tr_b16 v[8:9], v210 offset:128
	ds_read_b64_tr_b16 v[10:11], v210 offset:2688
	ds_read_b64_tr_b16 v[4:5], v210 offset:192
	ds_read_b64_tr_b16 v[6:7], v210 offset:2752
	s_waitcnt lgkmcnt(8)
	v_mfma_f32_32x32x16_bf16 v[98:113], v[224:227], v[126:129], v[98:113]
	s_cbranch_vccz .Lmy_maskB
